# v29 + removed the 30 asm-artifact s_nop 0 pads between chained v_max3 in the MLA / forgetting-attention softmax
# speedup vs baseline: 1.0051x; 1.0051x over previous
; #define LAS __attribute__((address_space(3)))
; template <int TYPE  >
; __device__ __forceinline__ void attn_item(const Params& P, const int b, const int h, const int qt, LAS unsigned char* lds) {
;     ...
;     for (int it = 0; it < NT; ++it) {
;         const int kt = AT_TILE(it);
;         if (it + 1 < NT) at_waitv<NI>(); else at_waitv<0>();
;         AT_BAR();
;         if (TYPE == 2 && it > 0) { const LAS int* fl = (const LAS int*)(lds + FLAGS + ((it - 1) & 1) * 32);
;             if (fl[0] & fl[1] & fl[2] & fl[3] & fl[4] & fl[5] & fl[6] & fl[7]) break; }
;         if (it + 2 < NT) AT_ISSUE(AT_TILE(it + 2), so2);
;         if (kt <= wlast && !(TYPE == 2 && wv_done)) {
;             if (!have_s) { AT_QK(so); }
;             const unsigned vb = a0v + so;
;             bf16x8 vf0[4], vf1[4], vf2[4], vf3[4];
;     ...
;             AT_RV(vf0, 0);
;             __builtin_amdgcn_sched_barrier(0);
;             const bool diag = (kt == wlast);
;             const int key0 = kt * 64 + 8 * hh;
;             if (TYPE == 2) {
;                 if (diag) {
; #pragma unroll
;                     for (int i = 0; i < 16; ++i) { const int key = key0 + 16 * (i >> 3) + (i & 7); if (key >= tq) s0[i] = -1e30f; if (key + 32 >= tq) s1[i] = -1e30f; } }
;                 sb_sub(s1, carry, hh); sb_sub(s0, carry, hh);
;             } else {
;                 if (TYPE == 1) { const LAS float* fb = (const LAS float*)(lds + so + KREG + VREG + wid * 256) + 8 * hh;
; #pragma unroll
;                     for (int j = 0; j < 8; ++j) {
;                         const f32x2 b0 = *(const LAS f32x2*)(fb + 16 * (j >> 2) + 2 * (j & 3)), b1 = *(const LAS f32x2*)(fb + 32 + 16 * (j >> 2) + 2 * (j & 3));
;                         const f32x2 x0 = pk_sub((f32x2){s0[2 * j], s0[2 * j + 1]}, b0), x1 = pk_sub((f32x2){s1[2 * j], s1[2 * j + 1]}, b1);
;                         s0[2 * j] = x0[0]; s0[2 * j + 1] = x0[1]; s1[2 * j] = x1[0]; s1[2 * j + 1] = x1[1]; }
;                     if (diag) {
; #pragma unroll
;                         for (int i = 0; i < 16; ++i) { const int key = key0 + 16 * (i >> 3) + (i & 7); if (key > tq) s0[i] = -1e30f; if (key + 32 > tq) s1[i] = -1e30f; } } }
;                 float mx = m_run;
; #pragma unroll
;                 for (int i = 0; i < 16; ++i) mx = max3_(mx, s0[i], s1[i]);
;                 asm volatile("s_nop 1" : "+v"(mx));
;                 const float mnew = swap_max(mx);
.LBB0_1128:
	s_waitcnt vmcnt(5)
	s_add_i32 s12, s10, 0
	s_barrier
	s_cmp_gt_i32 s11, s3
	s_cbranch_scc1 .LBB0_1132
	v_add_u32_e32 v0, s2, v230
	v_add_u32_e32 v214, 0, v0
	v_xad_u32 v215, v0, 32, 0
	v_xad_u32 v231, v0, 64, 0
	v_xor_b32_e32 v0, 0x60, v0
	v_add_u32_e32 v0, 0, v0
	ds_read_b128 v[146:149], v231
	ds_read_b128 v[150:153], v231 offset:12288
	ds_read_b128 v[154:157], v0
	ds_read_b128 v[158:161], v0 offset:12288
	ds_read_b128 v[66:69], v214
	ds_read_b128 v[192:195], v214 offset:128
	ds_read_b128 v[70:73], v214 offset:12288
	ds_read_b128 v[196:199], v214 offset:12416
	ds_read_b128 v[200:203], v215
	ds_read_b128 v[204:207], v215 offset:128
	ds_read_b128 v[236:239], v215 offset:12288
	ds_read_b128 v[240:243], v215 offset:12416
	s_setprio 1
	s_waitcnt lgkmcnt(0)
	v_mfma_f32_32x32x16_bf16 v[82:97], v[66:69], v[142:145], 0
	v_mfma_f32_32x32x16_bf16 v[66:81], v[70:73], v[142:145], 0
	v_mfma_f32_32x32x16_bf16 v[82:97], v[200:203], v[138:141], v[82:97]
	v_mfma_f32_32x32x16_bf16 v[66:81], v[236:239], v[138:141], v[66:81]
	v_mfma_f32_32x32x16_bf16 v[82:97], v[146:149], v[134:137], v[82:97]
	v_mfma_f32_32x32x16_bf16 v[66:81], v[150:153], v[134:137], v[66:81]
	s_setprio 0
	ds_read_b128 v[146:149], v231 offset:128
	ds_read_b128 v[150:153], v231 offset:12416
	ds_read_b128 v[200:203], v0 offset:128
	ds_read_b128 v[236:239], v0 offset:12416
	ds_read_b128 v[244:247], v214 offset:256
	ds_read_b128 v[248:251], v214 offset:12544
	s_setprio 1
	v_mfma_f32_32x32x16_bf16 v[82:97], v[154:157], v[130:133], v[82:97]
	v_mfma_f32_32x32x16_bf16 v[66:81], v[158:161], v[130:133], v[66:81]
	v_mfma_f32_32x32x16_bf16 v[82:97], v[192:195], v[126:129], v[82:97]
	v_mfma_f32_32x32x16_bf16 v[66:81], v[196:199], v[126:129], v[66:81]
	v_mfma_f32_32x32x16_bf16 v[82:97], v[204:207], v[122:125], v[82:97]
	v_mfma_f32_32x32x16_bf16 v[66:81], v[240:243], v[122:125], v[66:81]
	s_setprio 0
	ds_read_b128 v[154:157], v215 offset:256
	ds_read_b128 v[158:161], v215 offset:12544
	ds_read_b128 v[192:195], v231 offset:256
	ds_read_b128 v[196:199], v231 offset:12544
	ds_read_b128 v[204:207], v0 offset:256
	ds_read_b128 v[240:243], v0 offset:12544
	s_setprio 1
	s_waitcnt lgkmcnt(0)
	v_mfma_f32_32x32x16_bf16 v[82:97], v[146:149], v[114:117], v[82:97]
	v_mfma_f32_32x32x16_bf16 v[66:81], v[150:153], v[114:117], v[66:81]
	v_mfma_f32_32x32x16_bf16 v[82:97], v[200:203], v[110:113], v[82:97]
	v_mfma_f32_32x32x16_bf16 v[66:81], v[236:239], v[110:113], v[66:81]
	v_mfma_f32_32x32x16_bf16 v[82:97], v[244:247], v[118:121], v[82:97]
	v_mfma_f32_32x32x16_bf16 v[66:81], v[248:251], v[118:121], v[66:81]
	s_setprio 0
	s_setprio 1
	v_mfma_f32_32x32x16_bf16 v[82:97], v[154:157], v[106:109], v[82:97]
	v_mfma_f32_32x32x16_bf16 v[66:81], v[158:161], v[106:109], v[66:81]
	v_mfma_f32_32x32x16_bf16 v[82:97], v[192:195], v[102:105], v[82:97]
	v_mfma_f32_32x32x16_bf16 v[66:81], v[196:199], v[102:105], v[66:81]
	v_mfma_f32_32x32x16_bf16 v[82:97], v[204:207], v[98:101], v[82:97]
	v_mfma_f32_32x32x16_bf16 v[66:81], v[240:243], v[98:101], v[66:81]
	s_setprio 0
	v_add_u32_e32 v154, s2, v229
	v_add_u32_e32 v0, s2, v228
	v_xor_b32_e32 v155, 64, v154
	v_add_u32_e32 v0, 0, v0
	v_xor_b32_e32 v146, 32, v154
	v_add_u32_e32 v232, 0, v155
	v_xor_b32_e32 v154, 0x60, v154
	s_nop 7
	s_nop 7
	s_nop 3
	v_add_u32_e32 v231, 0, v146
	ds_read_b128 v[150:153], v0 offset:24576
	ds_read_b128 v[146:149], v231
	v_add_u32_e32 v233, 0, v154
	ds_read_b128 v[158:161], v232
	ds_read_b128 v[154:157], v233
	v_max3_f32 v192, v234, v82, v66
	v_max3_f32 v192, v192, v83, v67
	v_max3_f32 v192, v192, v84, v68
	v_max3_f32 v192, v192, v85, v69
	v_max3_f32 v192, v192, v86, v70
	v_max3_f32 v192, v192, v87, v71
	v_max3_f32 v192, v192, v88, v72
	v_max3_f32 v192, v192, v89, v73
	v_max3_f32 v192, v192, v90, v74
	v_max3_f32 v192, v192, v91, v75
	v_max3_f32 v192, v192, v92, v76
	v_max3_f32 v192, v192, v93, v77
	v_max3_f32 v192, v192, v94, v78
	v_max3_f32 v192, v192, v95, v79
	v_max3_f32 v192, v192, v96, v80
	v_max3_f32 v192, v192, v97, v81
	s_nop 0
	s_nop 1
	s_nop 0
	v_mov_b32_e32 v193, v192
	s_nop 1
	v_permlane32_swap_b32_e32 v192, v193
	v_max_f32_e32 v193, v193, v193
	v_max_f32_e32 v192, v192, v192
	v_max_f32_e32 v192, v192, v193
	v_cmp_gt_f32_e32 vcc, v192, v234
	v_mov_b32_e32 v193, v192
	v_pk_add_f32 v[206:207], v[82:83], v[192:193] neg_lo:[0,1] neg_hi:[0,1]
	v_pk_add_f32 v[204:205], v[66:67], v[192:193] neg_lo:[0,1] neg_hi:[0,1]
	v_pk_add_f32 v[202:203], v[84:85], v[192:193] neg_lo:[0,1] neg_hi:[0,1]
	v_pk_add_f32 v[200:201], v[68:69], v[192:193] neg_lo:[0,1] neg_hi:[0,1]
	v_pk_add_f32 v[198:199], v[86:87], v[192:193] neg_lo:[0,1] neg_hi:[0,1]
	v_pk_add_f32 v[196:197], v[70:71], v[192:193] neg_lo:[0,1] neg_hi:[0,1]
	v_pk_add_f32 v[194:195], v[88:89], v[192:193] neg_lo:[0,1] neg_hi:[0,1]
	v_pk_add_f32 v[88:89], v[72:73], v[192:193] neg_lo:[0,1] neg_hi:[0,1]
	v_pk_add_f32 v[86:87], v[90:91], v[192:193] neg_lo:[0,1] neg_hi:[0,1]
	v_pk_add_f32 v[84:85], v[74:75], v[192:193] neg_lo:[0,1] neg_hi:[0,1]
	v_pk_add_f32 v[82:83], v[92:93], v[192:193] neg_lo:[0,1] neg_hi:[0,1]
	v_pk_add_f32 v[74:75], v[76:77], v[192:193] neg_lo:[0,1] neg_hi:[0,1]
	v_pk_add_f32 v[72:73], v[94:95], v[192:193] neg_lo:[0,1] neg_hi:[0,1]
	v_pk_add_f32 v[70:71], v[78:79], v[192:193] neg_lo:[0,1] neg_hi:[0,1]
	v_pk_add_f32 v[68:69], v[96:97], v[192:193] neg_lo:[0,1] neg_hi:[0,1]
	v_pk_add_f32 v[66:67], v[80:81], v[192:193] neg_lo:[0,1] neg_hi:[0,1]
	s_cbranch_vccz .LBB0_1131
; __device__ __forceinline__ float exp2_(float x) { return __builtin_amdgcn_exp2f(x); }
; template <int TYPE  >
; __device__ __forceinline__ void attn_item(const Params& P, const int b, const int h, const int qt, LAS unsigned char* lds) {
;     ...
;                 if (__any(mnew > m_run)) {
;                     const float alpha = exp2_(m_run - mnew);
;                     l_run *= alpha; o0 *= alpha; o1 *= alpha; o2 *= alpha; o3 *= alpha;
;                 }
	v_sub_f32_e32 v76, v234, v192
	v_exp_f32_e32 v76, v76
	s_nop 0
	v_mul_f32_e32 v227, v227, v76
	v_pk_mul_f32 v[64:65], v[64:65], v[76:77] op_sel_hi:[1,0]
	v_pk_mul_f32 v[62:63], v[62:63], v[76:77] op_sel_hi:[1,0]
	v_pk_mul_f32 v[60:61], v[60:61], v[76:77] op_sel_hi:[1,0]
	v_pk_mul_f32 v[58:59], v[58:59], v[76:77] op_sel_hi:[1,0]
	v_pk_mul_f32 v[56:57], v[56:57], v[76:77] op_sel_hi:[1,0]
	v_pk_mul_f32 v[54:55], v[54:55], v[76:77] op_sel_hi:[1,0]
	v_pk_mul_f32 v[52:53], v[52:53], v[76:77] op_sel_hi:[1,0]
	v_pk_mul_f32 v[50:51], v[50:51], v[76:77] op_sel_hi:[1,0]
	v_pk_mul_f32 v[48:49], v[48:49], v[76:77] op_sel_hi:[1,0]
	v_pk_mul_f32 v[46:47], v[46:47], v[76:77] op_sel_hi:[1,0]
	v_pk_mul_f32 v[44:45], v[44:45], v[76:77] op_sel_hi:[1,0]
	v_pk_mul_f32 v[42:43], v[42:43], v[76:77] op_sel_hi:[1,0]
	v_pk_mul_f32 v[40:41], v[40:41], v[76:77] op_sel_hi:[1,0]
	v_pk_mul_f32 v[38:39], v[38:39], v[76:77] op_sel_hi:[1,0]
	v_pk_mul_f32 v[36:37], v[36:37], v[76:77] op_sel_hi:[1,0]
	v_pk_mul_f32 v[34:35], v[34:35], v[76:77] op_sel_hi:[1,0]
	v_pk_mul_f32 v[32:33], v[32:33], v[76:77] op_sel_hi:[1,0]
	v_pk_mul_f32 v[30:31], v[30:31], v[76:77] op_sel_hi:[1,0]
	v_pk_mul_f32 v[28:29], v[28:29], v[76:77] op_sel_hi:[1,0]
	v_pk_mul_f32 v[26:27], v[26:27], v[76:77] op_sel_hi:[1,0]
	v_pk_mul_f32 v[24:25], v[24:25], v[76:77] op_sel_hi:[1,0]
	v_pk_mul_f32 v[22:23], v[22:23], v[76:77] op_sel_hi:[1,0]
	v_pk_mul_f32 v[20:21], v[20:21], v[76:77] op_sel_hi:[1,0]
	v_pk_mul_f32 v[18:19], v[18:19], v[76:77] op_sel_hi:[1,0]
	v_pk_mul_f32 v[16:17], v[16:17], v[76:77] op_sel_hi:[1,0]
	v_pk_mul_f32 v[14:15], v[14:15], v[76:77] op_sel_hi:[1,0]
	v_pk_mul_f32 v[12:13], v[12:13], v[76:77] op_sel_hi:[1,0]
	v_pk_mul_f32 v[10:11], v[10:11], v[76:77] op_sel_hi:[1,0]
	v_pk_mul_f32 v[8:9], v[8:9], v[76:77] op_sel_hi:[1,0]
	v_pk_mul_f32 v[6:7], v[6:7], v[76:77] op_sel_hi:[1,0]
	v_pk_mul_f32 v[4:5], v[4:5], v[76:77] op_sel_hi:[1,0]
	v_pk_mul_f32 v[2:3], v[2:3], v[76:77] op_sel_hi:[1,0]

; __device__ __forceinline__ float exp2_(float x) { return __builtin_amdgcn_exp2f(x); }
; __device__ __forceinline__ float max3_(float a, float b, float c) { float r; asm("v_max3_f32 %0, %1, %2, %3" : "=v"(r) : "v"(a), "v"(b), "v"(c)); return r; }
; __device__ __forceinline__ f32x2 pk_sub(f32x2 a, f32x2 b) { f32x2 r; asm("v_pk_add_f32 %0, %1, %2 neg_lo:[0,1] neg_hi:[0,1]" : "=v"(r) : "v"(a), "v"(b)); return r; }
; __device__ __forceinline__ float swap_max(float x) { auto rr = __builtin_amdgcn_permlane32_swap(__float_as_uint(x), __float_as_uint(x), false, false); return fmaxf(__uint_as_float(rr[0]), __uint_as_float(rr[1])); }
; template <int TYPE  >
; __device__ __forceinline__ void attn_item(const Params& P, const int b, const int h, const int qt, LAS unsigned char* lds) {
;     ...
;                 float mx = m_run;
; #pragma unroll
;                 for (int i = 0; i < 16; ++i) mx = max3_(mx, s0[i], s1[i]);
;                 asm volatile("s_nop 1" : "+v"(mx));
;                 const float mnew = swap_max(mx);
;                 const f32x2 mm = {mnew, mnew}; f32x2 rs2 = {0.f, 0.f};
; #pragma unroll
;                 for (int j = 0; j < 8; ++j) { const f32x2 x0 = pk_sub((f32x2){s0[2 * j], s0[2 * j + 1]}, mm), x1 = pk_sub((f32x2){s1[2 * j], s1[2 * j + 1]}, mm);
;                     s0[2 * j] = exp2_(x0[0]); s0[2 * j + 1] = exp2_(x0[1]); s1[2 * j] = exp2_(x1[0]); s1[2 * j + 1] = exp2_(x1[1]);
;                     rs2 += (f32x2){s0[2 * j], s0[2 * j + 1]} + (f32x2){s1[2 * j], s1[2 * j + 1]}; }
;                 const float rs = rs2[0] + rs2[1];
;                 if (__any(mnew > m_run)) {
;                     const float alpha = exp2_(m_run - mnew);
;                     l_run *= alpha; o0 *= alpha; o1 *= alpha; o2 *= alpha; o3 *= alpha;
;                 }
.LBB0_1156:
	v_max3_f32 v66, v196, v82, v158
	v_max3_f32 v66, v66, v83, v159
	v_max3_f32 v66, v66, v156, v84
	v_max3_f32 v66, v66, v157, v85
	v_max3_f32 v66, v66, v68, v160
	v_max3_f32 v66, v66, v69, v161
	v_max3_f32 v66, v66, v86, v70
	v_max3_f32 v66, v66, v87, v71
	v_max3_f32 v66, v66, v72, v90
	v_max3_f32 v66, v66, v73, v91
	v_max3_f32 v66, v66, v88, v74
	v_max3_f32 v66, v66, v89, v75
	v_max3_f32 v66, v66, v76, v94
	v_max3_f32 v66, v66, v77, v95
	v_max3_f32 v66, v66, v92, v78
	v_max3_f32 v66, v66, v93, v79
	s_nop 0
	s_nop 1
	s_nop 0
	v_mov_b32_e32 v67, v66
	s_nop 1
	v_permlane32_swap_b32_e32 v66, v67
	v_max_f32_e32 v67, v67, v67
	v_max_f32_e32 v66, v66, v66
	v_max_f32_e32 v66, v66, v67
	v_cmp_gt_f32_e32 vcc, v66, v196
	v_mov_b32_e32 v67, v66
	v_pk_add_f32 v[184:185], v[82:83], v[66:67] neg_lo:[0,1] neg_hi:[0,1]
	v_pk_add_f32 v[182:183], v[158:159], v[66:67] neg_lo:[0,1] neg_hi:[0,1]
	v_pk_add_f32 v[180:181], v[156:157], v[66:67] neg_lo:[0,1] neg_hi:[0,1]
	v_pk_add_f32 v[178:179], v[84:85], v[66:67] neg_lo:[0,1] neg_hi:[0,1]
	v_pk_add_f32 v[176:177], v[68:69], v[66:67] neg_lo:[0,1] neg_hi:[0,1]
	v_pk_add_f32 v[158:159], v[160:161], v[66:67] neg_lo:[0,1] neg_hi:[0,1]
	v_pk_add_f32 v[156:157], v[86:87], v[66:67] neg_lo:[0,1] neg_hi:[0,1]
	v_pk_add_f32 v[96:97], v[70:71], v[66:67] neg_lo:[0,1] neg_hi:[0,1]
	v_pk_add_f32 v[86:87], v[72:73], v[66:67] neg_lo:[0,1] neg_hi:[0,1]
	v_pk_add_f32 v[84:85], v[90:91], v[66:67] neg_lo:[0,1] neg_hi:[0,1]
	v_pk_add_f32 v[82:83], v[88:89], v[66:67] neg_lo:[0,1] neg_hi:[0,1]
	v_pk_add_f32 v[80:81], v[74:75], v[66:67] neg_lo:[0,1] neg_hi:[0,1]
	v_pk_add_f32 v[74:75], v[76:77], v[66:67] neg_lo:[0,1] neg_hi:[0,1]
	v_pk_add_f32 v[72:73], v[94:95], v[66:67] neg_lo:[0,1] neg_hi:[0,1]
	v_pk_add_f32 v[70:71], v[92:93], v[66:67] neg_lo:[0,1] neg_hi:[0,1]
	v_pk_add_f32 v[68:69], v[78:79], v[66:67] neg_lo:[0,1] neg_hi:[0,1]
	s_cbranch_vccz .LBB0_1158
	v_sub_f32_e32 v67, v196, v66
	v_exp_f32_e32 v76, v67
	s_nop 0
	v_mul_f32_e32 v192, v192, v76
	v_pk_mul_f32 v[64:65], v[64:65], v[76:77] op_sel_hi:[1,0]
	v_pk_mul_f32 v[62:63], v[62:63], v[76:77] op_sel_hi:[1,0]
	v_pk_mul_f32 v[60:61], v[60:61], v[76:77] op_sel_hi:[1,0]
	v_pk_mul_f32 v[58:59], v[58:59], v[76:77] op_sel_hi:[1,0]
	v_pk_mul_f32 v[56:57], v[56:57], v[76:77] op_sel_hi:[1,0]
	v_pk_mul_f32 v[54:55], v[54:55], v[76:77] op_sel_hi:[1,0]
	v_pk_mul_f32 v[52:53], v[52:53], v[76:77] op_sel_hi:[1,0]
	v_pk_mul_f32 v[50:51], v[50:51], v[76:77] op_sel_hi:[1,0]
	v_pk_mul_f32 v[48:49], v[48:49], v[76:77] op_sel_hi:[1,0]
	v_pk_mul_f32 v[46:47], v[46:47], v[76:77] op_sel_hi:[1,0]
	v_pk_mul_f32 v[44:45], v[44:45], v[76:77] op_sel_hi:[1,0]
	v_pk_mul_f32 v[42:43], v[42:43], v[76:77] op_sel_hi:[1,0]
	v_pk_mul_f32 v[40:41], v[40:41], v[76:77] op_sel_hi:[1,0]
	v_pk_mul_f32 v[38:39], v[38:39], v[76:77] op_sel_hi:[1,0]
	v_pk_mul_f32 v[36:37], v[36:37], v[76:77] op_sel_hi:[1,0]
	v_pk_mul_f32 v[34:35], v[34:35], v[76:77] op_sel_hi:[1,0]
	v_pk_mul_f32 v[32:33], v[32:33], v[76:77] op_sel_hi:[1,0]
	v_pk_mul_f32 v[30:31], v[30:31], v[76:77] op_sel_hi:[1,0]
	v_pk_mul_f32 v[28:29], v[28:29], v[76:77] op_sel_hi:[1,0]
	v_pk_mul_f32 v[26:27], v[26:27], v[76:77] op_sel_hi:[1,0]
	v_pk_mul_f32 v[24:25], v[24:25], v[76:77] op_sel_hi:[1,0]
	v_pk_mul_f32 v[22:23], v[22:23], v[76:77] op_sel_hi:[1,0]
	v_pk_mul_f32 v[20:21], v[20:21], v[76:77] op_sel_hi:[1,0]
	v_pk_mul_f32 v[18:19], v[18:19], v[76:77] op_sel_hi:[1,0]
	v_pk_mul_f32 v[16:17], v[16:17], v[76:77] op_sel_hi:[1,0]
	v_pk_mul_f32 v[14:15], v[14:15], v[76:77] op_sel_hi:[1,0]
	v_pk_mul_f32 v[12:13], v[12:13], v[76:77] op_sel_hi:[1,0]
	v_pk_mul_f32 v[10:11], v[10:11], v[76:77] op_sel_hi:[1,0]
	v_pk_mul_f32 v[8:9], v[8:9], v[76:77] op_sel_hi:[1,0]
	v_pk_mul_f32 v[6:7], v[6:7], v[76:77] op_sel_hi:[1,0]
	v_pk_mul_f32 v[4:5], v[4:5], v[76:77] op_sel_hi:[1,0]
	v_pk_mul_f32 v[2:3], v[2:3], v[76:77] op_sel_hi:[1,0]
